# cvhost: hosted consume + stores issued at the end of the tile just before the step-A wait (no LDS-DMA in flight), step-A wait vmcnt(2), step-B wait vmcnt(3)
# speedup vs baseline: 1.0067x; 1.0018x over previous
; template <int NB>
; __device__ __forceinline__ void p0_batch(int it0, int stride, int lane, const P0Ptrs& a) {
;     ...
;     for (int q = 0; q < NB; ++q) {
;         const float gs = d[q].gs; const bool hk = d[q].ks != nullptr;
;         const f32x4 t0 = hk ? s0[q] * gs : (f32x4){gs, gs, gs, gs}, t1 = hk ? s1[q] * gs : (f32x4){gs, gs, gs, gs};
; #pragma unroll
;         for (int i = 0; i < 4; ++i) { v[q][i] *= t0[i]; v[q][4 + i] *= t1[i]; }
.LBB0_759:
	s_add_i32 s98, s87, -1
	s_cmp_gt_u32 s98, 19
	s_cbranch_scc1 .Lcv_predone
	s_waitcnt vmcnt(5)
	s_cmp_gt_u32 s32, 6
	s_cbranch_scc1 .Lcv_nomul
	v_mul_f32_e32 v238, v237, v238
	v_mul_f32_e32 v239, v237, v239
	v_mul_f32_e32 v240, v237, v240
	v_mul_f32_e32 v241, v237, v241
	v_mul_f32_e32 v242, v237, v242
	v_mul_f32_e32 v243, v237, v243
	v_mul_f32_e32 v244, v237, v244
	v_mul_f32_e32 v245, v237, v245

.Lcv_predone:
	v_lshl_add_u64 v[112:113], s[28:29], 0, v[146:147]
	s_mov_b64 s[54:55], 0x18fc0000
	s_mov_b32 m0, s78
	v_lshl_add_u64 v[100:101], v[112:113], 0, s[54:55]
	s_add_i32 s98, s87, -1
	s_cmp_gt_u32 s98, 19
	s_cbranch_scc1 .Lcv_wa0
	s_waitcnt vmcnt(2)
	s_branch .Lcv_wad

; __device__ __forceinline__ P0Desc p0_desc(int r, int lane, const P0Ptrs& a) {
;     const int kk = lane >> 3, n4 = (lane & 7) * 4; P0Desc d; d.gs = 1.f;
;     int kb, n, sc, nsrc, ldt; const float* W; bf16_t* WT; const float* ks;
;     if (r < F_O) { kb = r >> 6; n = 32 * (r & 63) + n4; sc = n; W = a.w_o; nsrc = 2048; WT = a.WoT; ldt = 2048; ks = (kb < 16) ? a.on_a : (a.on_c - 1024); }
;     else if ((r -= F_O) < F_UP) { kb = r / 352; n = 32 * (r % 352) + n4; sc = ((n >> 7) & 1) * DFF + (n >> 8) * 128 + (n & 127); W = a.w_up; nsrc = 2 * DFF; WT = a.WupT; ldt = 2048; ks = a.ffn_g; }
;     else if ((r -= F_UP) < F_DN) { kb = r >> 6; n = 32 * (r & 63) + n4; sc = n; W = a.w_dn; nsrc = 2048; WT = a.WdT; ldt = DFF; ks = nullptr; }
;     else if ((r -= F_DN) < F_IN) { kb = r >> 7; n = 32 * (r & 127) + n4;
;         if (n < 1024) sc = n; else if (n < 2048) sc = n + 64; else sc = (((n >> 7) & 1) ? 3136 : 2112) + 128 * ((n - 2048) >> 8) + (n & 127);
;         W = a.w_in; nsrc = INW; WT = a.WinT; ldt = 2048; ks = a.attn_g; }
;     else if ((r -= F_IN) < F_Q) { kb = r >> 5; n = 32 * (6 * ((r & 31) >> 2) + (r & 3)) + n4; sc = n; W = a.w_qb; nsrc = 1536; WT = a.WqT; ldt = 2048; ks = a.qa_g; d.gs = QSCALE; }
;     else { r -= F_Q; kb = r >> 6; n = 32 * (r & 63) + n4; sc = n; W = a.w_kvb; nsrc = 2048; WT = a.WkvT; ldt = 2048; ks = a.kva_g; }
;     const int k0 = 64 * kb + 8 * kk;
;     d.src = W + (size_t)k0 * nsrc + sc; d.nsrc = nsrc; d.dst = WT + (size_t)n * ldt + k0; d.ldt = ldt; d.ks = ks ? ks + k0 : nullptr;
;     return d;
; }
.Lcv_wad:
	s_barrier
	global_load_lds_dwordx4 v[100:101], off
	v_lshl_add_u64 v[100:101], v[112:113], 0, s[38:39]
	s_add_i32 m0, s78, 0x2000
	v_lshl_add_u64 v[136:137], s[28:29], 0, v[144:145]
	global_load_lds_dwordx4 v[100:101], off
	v_lshl_add_u64 v[100:101], v[136:137], 0, s[40:41]
	s_add_i32 m0, s78, 0x4000
	v_lshl_add_u64 v[134:135], s[28:29], 0, v[148:149]
	global_load_lds_dwordx4 v[100:101], off
	v_lshl_add_u64 v[100:101], v[134:135], 0, s[42:43]
	s_mov_b32 m0, s58
	global_load_lds_dwordx4 v[100:101], off
	v_lshl_add_u64 v[100:101], v[134:135], 0, s[44:45]
	s_mov_b32 m0, s77
	global_load_lds_dwordx4 v[100:101], off
	s_cmp_gt_u32 s87, 20
	s_cbranch_scc1 .Lcv_done
	s_cmp_gt_u32 s87, 19
	s_cbranch_scc1 .Lcv_inc
	s_and_b32 s98, s87, 3
	s_cmp_lg_u32 s98, 0
	s_cbranch_scc1 .Lcv_loads
	s_add_i32 s32, s32, 1
	v_readfirstlane_b32 s99, v0
	s_waitcnt lgkmcnt(0)
	s_and_b32 s98, s2, 0xff
	s_lshr_b32 s90, s98, 3
	s_and_b32 s98, s98, 7
	s_lshl_b32 s98, s98, 3
	s_lshr_b32 s99, s99, 6
	s_add_i32 s91, s98, s99
	s_cmp_eq_u32 s32, 0
	s_cbranch_scc1 .Lcv_t0
	s_cmp_lt_u32 s32, 7
	s_cbranch_scc1 .Lcv_t1
	s_add_i32 s98, s32, -7
	s_lshl_b32 s98, s98, 5
	s_add_i32 s90, s90, s98
	s_cmp_ge_u32 s90, 0x58
	s_cselect_b32 s98, 32, 0
	s_sub_i32 s90, s90, s98
	s_lshl_b32 s98, s90, 19
	s_lshl_b32 s99, s91, 7
	s_add_i32 s98, s98, s99
	s_add_u32 s88, s88, s98
	s_addc_u32 s89, s89, 0
	s_mul_i32 s98, s91, 0x58000
	s_lshl_b32 s99, s90, 7
	s_add_i32 s98, s98, s99
	s_add_i32 s98, s98, 0x6900000
	s_add_u32 s92, s28, s98
	s_addc_u32 s93, s29, 0
	s_mov_b32 s90, 0x2000
	s_mov_b32 s91, 0x2c00
	s_branch .Lcv_s2done
